# G3/G5 residual epilogues: residual loads batched 8 at a time with counted vmcnt instead of one load-wait-store chain per element; ATT2F epilogue gain loads hoisted
# speedup vs baseline: 1.0578x; 1.0074x over previous
; __device__ __forceinline__ unsigned cvt_pk_bf16(float lo, float hi) { unsigned r; asm volatile("v_cvt_pk_bf16_f32 %0, %1, %2" : "=v"(r) : "v"(lo), "v"(hi)); return r; }
; template <bool DIFF, bool FIXED, bool F32SRC> ...
;     ...
;     if (wact && sub == 0 && qvalid) {
;         bf16_t* op = O + (size_t)qrow * PITCH + u.h * HW;
; #pragma unroll
;         for (int db = 0; db < NDB; ++db)
; #pragma unroll
;             for (int r4 = 0; r4 < 4; ++r4) {
;                 const int d = 32 * db + 8 * r4 + 4 * hi;
;                 f32x4 v = (f32x4){o[db][4 * r4], o[db][4 * r4 + 1], o[db][4 * r4 + 2], o[db][4 * r4 + 3]} * sc;
;                 if (DIFF) v = v * *(const f32x4*)(subln_g + d);
;                 u32x2 pk; pk.x = cvt_pk_bf16(v[0], v[1]); pk.y = cvt_pk_bf16(v[2], v[3]);
;                 *(u32x2*)(op + d) = pk;
;             }
.LBB0_466:
	s_and_b64 s[10:11], s[0:1], s[10:11]
	s_and_saveexec_b64 s[0:1], s[10:11]
	s_cbranch_execz .LBB0_468
	v_lshlrev_b32_e32 v67, 2, v194
	global_load_dwordx4 v[98:101], v67, s[14:15]
	global_load_dwordx4 v[102:105], v67, s[14:15] offset:32
	global_load_dwordx4 v[106:109], v67, s[14:15] offset:64
	global_load_dwordx4 v[110:113], v67, s[14:15] offset:96
	global_load_dwordx4 v[114:117], v67, s[14:15] offset:128
	global_load_dwordx4 v[118:121], v67, s[14:15] offset:160
	global_load_dwordx4 v[122:125], v67, s[14:15] offset:192
	global_load_dwordx4 v[126:129], v67, s[14:15] offset:224
	global_load_dwordx4 v[162:165], v67, s[14:15] offset:256
	global_load_dwordx4 v[166:169], v67, s[14:15] offset:288
	global_load_dwordx4 v[170:173], v67, s[14:15] offset:320
	global_load_dwordx4 v[174:177], v67, s[14:15] offset:352
	global_load_dwordx4 v[178:181], v67, s[14:15] offset:384
	global_load_dwordx4 v[182:185], v67, s[14:15] offset:416
	global_load_dwordx4 v[186:189], v67, s[14:15] offset:448
	global_load_dwordx4 v[190:193], v67, s[14:15] offset:480
	v_pk_mul_f32 v[72:73], v[50:51], v[66:67] op_sel_hi:[1,0]
	v_lshlrev_b32_e32 v0, 1, v194
	v_pk_mul_f32 v[52:53], v[52:53], v[66:67] op_sel_hi:[1,0]
	v_lshl_add_u64 v[50:51], v[130:131], 0, v[0:1]
	v_pk_mul_f32 v[34:35], v[34:35], v[66:67] op_sel_hi:[1,0]
	v_pk_mul_f32 v[36:37], v[36:37], v[66:67] op_sel_hi:[1,0]
	v_pk_mul_f32 v[38:39], v[38:39], v[66:67] op_sel_hi:[1,0]
	v_pk_mul_f32 v[40:41], v[40:41], v[66:67] op_sel_hi:[1,0]
	v_pk_mul_f32 v[18:19], v[18:19], v[66:67] op_sel_hi:[1,0]
	v_pk_mul_f32 v[20:21], v[20:21], v[66:67] op_sel_hi:[1,0]
	v_pk_mul_f32 v[22:23], v[22:23], v[66:67] op_sel_hi:[1,0]
	v_pk_mul_f32 v[24:25], v[24:25], v[66:67] op_sel_hi:[1,0]
	v_pk_mul_f32 v[2:3], v[2:3], v[66:67] op_sel_hi:[1,0]
	v_pk_mul_f32 v[4:5], v[4:5], v[66:67] op_sel_hi:[1,0]
	v_pk_mul_f32 v[6:7], v[6:7], v[66:67] op_sel_hi:[1,0]
	v_pk_mul_f32 v[8:9], v[8:9], v[66:67] op_sel_hi:[1,0]
	s_waitcnt vmcnt(0)
	v_pk_mul_f32 v[68:69], v[72:73], v[98:99]
	v_pk_mul_f32 v[52:53], v[52:53], v[100:101]
	v_cvt_pk_bf16_f32 v68, v68, v69
	s_nop 0
	v_cvt_pk_bf16_f32 v69, v52, v53
	global_store_dwordx2 v[50:51], v[68:69], off
	v_pk_mul_f32 v[52:53], v[54:55], v[66:67] op_sel_hi:[1,0]
	v_pk_mul_f32 v[54:55], v[56:57], v[66:67] op_sel_hi:[1,0]
	v_pk_mul_f32 v[56:57], v[58:59], v[66:67] op_sel_hi:[1,0]
	v_pk_mul_f32 v[58:59], v[60:61], v[66:67] op_sel_hi:[1,0]
	v_pk_mul_f32 v[52:53], v[52:53], v[102:103]
	v_pk_mul_f32 v[54:55], v[54:55], v[104:105]
	v_cvt_pk_bf16_f32 v52, v52, v53
	s_nop 0
	v_cvt_pk_bf16_f32 v53, v54, v55
	global_store_dwordx2 v[50:51], v[52:53], off offset:16
	v_pk_mul_f32 v[52:53], v[56:57], v[106:107]
	v_pk_mul_f32 v[54:55], v[58:59], v[108:109]
	v_cvt_pk_bf16_f32 v52, v52, v53
	v_pk_mul_f32 v[56:57], v[62:63], v[66:67] op_sel_hi:[1,0]
	v_cvt_pk_bf16_f32 v53, v54, v55
	global_store_dwordx2 v[50:51], v[52:53], off offset:32
	v_pk_mul_f32 v[58:59], v[64:65], v[66:67] op_sel_hi:[1,0]
	v_pk_mul_f32 v[52:53], v[56:57], v[110:111]
	v_pk_mul_f32 v[54:55], v[58:59], v[112:113]
	v_cvt_pk_bf16_f32 v52, v52, v53
	s_nop 0
	v_cvt_pk_bf16_f32 v53, v54, v55
	global_store_dwordx2 v[50:51], v[52:53], off offset:48
	v_pk_mul_f32 v[34:35], v[34:35], v[114:115]
	v_pk_mul_f32 v[36:37], v[36:37], v[116:117]
	v_cvt_pk_bf16_f32 v34, v34, v35
	s_nop 0
	v_cvt_pk_bf16_f32 v35, v36, v37
	global_store_dwordx2 v[50:51], v[34:35], off offset:64
	v_pk_mul_f32 v[34:35], v[38:39], v[118:119]
	v_pk_mul_f32 v[36:37], v[40:41], v[120:121]
	v_cvt_pk_bf16_f32 v34, v34, v35
	v_pk_mul_f32 v[38:39], v[42:43], v[66:67] op_sel_hi:[1,0]
	v_cvt_pk_bf16_f32 v35, v36, v37
	global_store_dwordx2 v[50:51], v[34:35], off offset:80
	v_pk_mul_f32 v[40:41], v[44:45], v[66:67] op_sel_hi:[1,0]
	v_pk_mul_f32 v[34:35], v[38:39], v[122:123]
	v_pk_mul_f32 v[36:37], v[40:41], v[124:125]
	v_cvt_pk_bf16_f32 v34, v34, v35
	v_pk_mul_f32 v[38:39], v[46:47], v[66:67] op_sel_hi:[1,0]
	v_cvt_pk_bf16_f32 v35, v36, v37
	global_store_dwordx2 v[50:51], v[34:35], off offset:96
	v_pk_mul_f32 v[40:41], v[48:49], v[66:67] op_sel_hi:[1,0]
	v_pk_mul_f32 v[34:35], v[38:39], v[126:127]
	v_pk_mul_f32 v[36:37], v[40:41], v[128:129]
	v_cvt_pk_bf16_f32 v34, v34, v35
	s_nop 0
	v_cvt_pk_bf16_f32 v35, v36, v37
	global_store_dwordx2 v[50:51], v[34:35], off offset:112
	v_pk_mul_f32 v[18:19], v[18:19], v[162:163]
	v_pk_mul_f32 v[20:21], v[20:21], v[164:165]
	v_cvt_pk_bf16_f32 v18, v18, v19
	s_nop 0
	v_cvt_pk_bf16_f32 v19, v20, v21
	global_store_dwordx2 v[50:51], v[18:19], off offset:128
	v_pk_mul_f32 v[18:19], v[22:23], v[166:167]
	v_pk_mul_f32 v[20:21], v[24:25], v[168:169]
	v_cvt_pk_bf16_f32 v18, v18, v19
	v_pk_mul_f32 v[22:23], v[26:27], v[66:67] op_sel_hi:[1,0]
	v_cvt_pk_bf16_f32 v19, v20, v21
	global_store_dwordx2 v[50:51], v[18:19], off offset:144
	v_pk_mul_f32 v[24:25], v[28:29], v[66:67] op_sel_hi:[1,0]
	v_pk_mul_f32 v[18:19], v[22:23], v[170:171]
	v_pk_mul_f32 v[20:21], v[24:25], v[172:173]
	v_cvt_pk_bf16_f32 v18, v18, v19
	v_pk_mul_f32 v[22:23], v[30:31], v[66:67] op_sel_hi:[1,0]
	v_cvt_pk_bf16_f32 v19, v20, v21
	global_store_dwordx2 v[50:51], v[18:19], off offset:160
	v_pk_mul_f32 v[24:25], v[32:33], v[66:67] op_sel_hi:[1,0]
	v_pk_mul_f32 v[18:19], v[22:23], v[174:175]
	v_pk_mul_f32 v[20:21], v[24:25], v[176:177]
	v_cvt_pk_bf16_f32 v18, v18, v19
	s_nop 0
	v_cvt_pk_bf16_f32 v19, v20, v21
	global_store_dwordx2 v[50:51], v[18:19], off offset:176
	v_pk_mul_f32 v[2:3], v[2:3], v[178:179]
	v_pk_mul_f32 v[4:5], v[4:5], v[180:181]
	v_cvt_pk_bf16_f32 v2, v2, v3
	s_nop 0
	v_cvt_pk_bf16_f32 v3, v4, v5
	global_store_dwordx2 v[50:51], v[2:3], off offset:192
	v_pk_mul_f32 v[2:3], v[6:7], v[182:183]
	v_pk_mul_f32 v[4:5], v[8:9], v[184:185]
	v_cvt_pk_bf16_f32 v2, v2, v3
	v_pk_mul_f32 v[6:7], v[10:11], v[66:67] op_sel_hi:[1,0]
	v_cvt_pk_bf16_f32 v3, v4, v5
	global_store_dwordx2 v[50:51], v[2:3], off offset:208
	v_pk_mul_f32 v[8:9], v[12:13], v[66:67] op_sel_hi:[1,0]
	v_pk_mul_f32 v[2:3], v[6:7], v[186:187]
	v_pk_mul_f32 v[4:5], v[8:9], v[188:189]
	v_cvt_pk_bf16_f32 v2, v2, v3
	v_pk_mul_f32 v[6:7], v[14:15], v[66:67] op_sel_hi:[1,0]
	v_cvt_pk_bf16_f32 v3, v4, v5
	global_store_dwordx2 v[50:51], v[2:3], off offset:224
	v_pk_mul_f32 v[8:9], v[16:17], v[66:67] op_sel_hi:[1,0]
	v_pk_mul_f32 v[2:3], v[6:7], v[190:191]
	v_pk_mul_f32 v[4:5], v[8:9], v[192:193]
	v_cvt_pk_bf16_f32 v2, v2, v3
	s_nop 0
	v_cvt_pk_bf16_f32 v3, v4, v5
	global_store_dwordx2 v[50:51], v[2:3], off offset:240

;     __device__ __forceinline__ void operator()(AccRef acc, const pg8::Unit& u, int wr, int wc, int fr, int fq) const {
;         const int lc = u.pn * 256 + wc * 64 + fq * 8;
;         const float* sb = (u.pm >= 128) ? srcS - (size_t)MP * 1024 : srcP;
; #pragma unroll
;         for (int ai = 0; ai < 2; ++ai)
; #pragma unroll
;             for (int m = 0; m < 4; ++m) {
;                 const size_t off = (size_t)(u.pm * 256 + ai * 128 + wr * 64 + m * 16 + fr) * 1024 + lc;
; #pragma unroll
;                 for (int bj = 0; bj < 2; ++bj)
; #pragma unroll
;                     for (int n = 0; n < 2; ++n) { const f32x4 s = *(const f32x4*)(sb + off + bj * 32 + n * 4); *(f32x4*)(dst + off + bj * 32 + n * 4) = s + acc[ai][bj][m][n]; }
;             }
.LBB0_557:
	v_lshl_add_u32 v142, s61, 8, v144
	v_lshl_or_b32 v140, s62, 8, v162
	v_ashrrev_i32_e32 v143, 31, v142
	v_ashrrev_i32_e32 v141, 31, v140
	s_cmpk_gt_i32 s61, 0x7f
	s_cselect_b32 s25, s59, s54
	s_cselect_b32 s24, s58, s55
	v_readlane_b32 s70, v254, 55
	v_readlane_b32 s80, v254, 57
	s_andn2_b64 vcc, exec, s[6:7]
	s_mov_b64 s[6:7], -1
	v_readlane_b32 s71, v254, 56
	v_readlane_b32 s81, v254, 58
	v_readlane_b32 s65, v254, 59
	s_movk_i32 s69, 0x2000
	v_lshlrev_b64 v[212:213], 10, v[142:143]
	v_lshl_add_u64 v[212:213], v[212:213], 0, v[140:141]
	v_lshlrev_b64 v[214:215], 2, v[212:213]
	v_lshl_add_u64 v[212:213], s[24:25], 0, v[214:215]
	v_lshl_add_u64 v[214:215], s[34:35], 0, v[214:215]
	global_load_dwordx4 v[164:167], v[212:213], off
	global_load_dwordx4 v[168:171], v[212:213], off offset:16
	global_load_dwordx4 v[172:175], v[212:213], off offset:128
	global_load_dwordx4 v[176:179], v[212:213], off offset:144
	v_add_u32_e32 v216, 0x10, v142
	v_ashrrev_i32_e32 v217, 31, v216
	v_lshlrev_b64 v[216:217], 10, v[216:217]
	v_lshl_add_u64 v[216:217], v[216:217], 0, v[140:141]
	v_lshlrev_b64 v[218:219], 2, v[216:217]
	v_lshl_add_u64 v[216:217], s[24:25], 0, v[218:219]
	v_lshl_add_u64 v[218:219], s[34:35], 0, v[218:219]
	global_load_dwordx4 v[180:183], v[216:217], off
	global_load_dwordx4 v[184:187], v[216:217], off offset:16
	global_load_dwordx4 v[188:191], v[216:217], off offset:128
	global_load_dwordx4 v[192:195], v[216:217], off offset:144
	s_waitcnt vmcnt(0)
	v_pk_add_f32 v[126:127], v[126:127], v[164:165]
	v_pk_add_f32 v[128:129], v[128:129], v[166:167]
	v_pk_add_f32 v[122:123], v[122:123], v[168:169]
	v_pk_add_f32 v[124:125], v[124:125], v[170:171]
	v_pk_add_f32 v[118:119], v[118:119], v[172:173]
	v_pk_add_f32 v[120:121], v[120:121], v[174:175]
	v_pk_add_f32 v[106:107], v[106:107], v[176:177]
	v_pk_add_f32 v[108:109], v[108:109], v[178:179]
	v_pk_add_f32 v[114:115], v[114:115], v[180:181]
	v_pk_add_f32 v[116:117], v[116:117], v[182:183]
	v_pk_add_f32 v[110:111], v[110:111], v[184:185]
	v_pk_add_f32 v[112:113], v[112:113], v[186:187]
	v_pk_add_f32 v[102:103], v[102:103], v[188:189]
	v_pk_add_f32 v[104:105], v[104:105], v[190:191]
	v_pk_add_f32 v[90:91], v[90:91], v[192:193]
	v_pk_add_f32 v[92:93], v[92:93], v[194:195]
	v_add_u32_e32 v220, 0x20, v142
	v_ashrrev_i32_e32 v221, 31, v220
	v_lshlrev_b64 v[220:221], 10, v[220:221]
	v_lshl_add_u64 v[220:221], v[220:221], 0, v[140:141]
	v_lshlrev_b64 v[222:223], 2, v[220:221]
	v_lshl_add_u64 v[220:221], s[24:25], 0, v[222:223]
	v_lshl_add_u64 v[222:223], s[34:35], 0, v[222:223]
	global_load_dwordx4 v[164:167], v[220:221], off
	global_load_dwordx4 v[168:171], v[220:221], off offset:16
	global_load_dwordx4 v[172:175], v[220:221], off offset:128
	global_load_dwordx4 v[176:179], v[220:221], off offset:144
	v_add_u32_e32 v224, 0x30, v142
	v_ashrrev_i32_e32 v225, 31, v224
	v_lshlrev_b64 v[224:225], 10, v[224:225]
	v_lshl_add_u64 v[224:225], v[224:225], 0, v[140:141]
	v_lshlrev_b64 v[226:227], 2, v[224:225]
	v_lshl_add_u64 v[224:225], s[24:25], 0, v[226:227]
	v_lshl_add_u64 v[226:227], s[34:35], 0, v[226:227]
	global_load_dwordx4 v[180:183], v[224:225], off
	global_load_dwordx4 v[184:187], v[224:225], off offset:16
	global_load_dwordx4 v[188:191], v[224:225], off offset:128
	global_load_dwordx4 v[192:195], v[224:225], off offset:144
	global_store_dwordx4 v[214:215], v[126:129], off
	global_store_dwordx4 v[214:215], v[122:125], off offset:16
	global_store_dwordx4 v[214:215], v[118:121], off offset:128
	global_store_dwordx4 v[214:215], v[106:109], off offset:144
	global_store_dwordx4 v[218:219], v[114:117], off
	global_store_dwordx4 v[218:219], v[110:113], off offset:16
	global_store_dwordx4 v[218:219], v[102:105], off offset:128
	global_store_dwordx4 v[218:219], v[90:93], off offset:144
	s_waitcnt vmcnt(8)
;     __device__ __forceinline__ void operator()(AccRef acc, const pg8::Unit& u, int wr, int wc, int fr, int fq) const {
;         const int lc = u.pn * 256 + wc * 64 + fq * 8;
;         const float* sb = (u.pm >= 128) ? srcS - (size_t)MP * 1024 : srcP;
; #pragma unroll
;         for (int ai = 0; ai < 2; ++ai)
; #pragma unroll
;             for (int m = 0; m < 4; ++m) {
;                 const size_t off = (size_t)(u.pm * 256 + ai * 128 + wr * 64 + m * 16 + fr) * 1024 + lc;
; #pragma unroll
;                 for (int bj = 0; bj < 2; ++bj)
; #pragma unroll
;                     for (int n = 0; n < 2; ++n) { const f32x4 s = *(const f32x4*)(sb + off + bj * 32 + n * 4); *(f32x4*)(dst + off + bj * 32 + n * 4) = s + acc[ai][bj][m][n]; }
;             }
	v_pk_add_f32 v[98:99], v[98:99], v[164:165]
	v_pk_add_f32 v[100:101], v[100:101], v[166:167]
	v_pk_add_f32 v[94:95], v[94:95], v[168:169]
	v_pk_add_f32 v[96:97], v[96:97], v[170:171]
	v_pk_add_f32 v[86:87], v[86:87], v[172:173]
	v_pk_add_f32 v[88:89], v[88:89], v[174:175]
	v_pk_add_f32 v[74:75], v[74:75], v[176:177]
	v_pk_add_f32 v[76:77], v[76:77], v[178:179]
	v_pk_add_f32 v[82:83], v[82:83], v[180:181]
	v_pk_add_f32 v[84:85], v[84:85], v[182:183]
	v_pk_add_f32 v[78:79], v[78:79], v[184:185]
	v_pk_add_f32 v[80:81], v[80:81], v[186:187]
	v_pk_add_f32 v[70:71], v[70:71], v[188:189]
	v_pk_add_f32 v[72:73], v[72:73], v[190:191]
	v_pk_add_f32 v[66:67], v[66:67], v[192:193]
	v_pk_add_f32 v[68:69], v[68:69], v[194:195]
	v_add_u32_e32 v212, 0x80, v142
	v_ashrrev_i32_e32 v213, 31, v212
	v_lshlrev_b64 v[212:213], 10, v[212:213]
	v_lshl_add_u64 v[212:213], v[212:213], 0, v[140:141]
	v_lshlrev_b64 v[214:215], 2, v[212:213]
	v_lshl_add_u64 v[212:213], s[24:25], 0, v[214:215]
	v_lshl_add_u64 v[214:215], s[34:35], 0, v[214:215]
	global_load_dwordx4 v[164:167], v[212:213], off
	global_load_dwordx4 v[168:171], v[212:213], off offset:16
	global_load_dwordx4 v[172:175], v[212:213], off offset:128
	global_load_dwordx4 v[176:179], v[212:213], off offset:144
	v_add_u32_e32 v216, 0x90, v142
	v_ashrrev_i32_e32 v217, 31, v216
	v_lshlrev_b64 v[216:217], 10, v[216:217]
	v_lshl_add_u64 v[216:217], v[216:217], 0, v[140:141]
	v_lshlrev_b64 v[218:219], 2, v[216:217]
	v_lshl_add_u64 v[216:217], s[24:25], 0, v[218:219]
	v_lshl_add_u64 v[218:219], s[34:35], 0, v[218:219]
	global_load_dwordx4 v[180:183], v[216:217], off
	global_load_dwordx4 v[184:187], v[216:217], off offset:16
	global_load_dwordx4 v[188:191], v[216:217], off offset:128
	global_load_dwordx4 v[192:195], v[216:217], off offset:144
	global_store_dwordx4 v[222:223], v[98:101], off
	global_store_dwordx4 v[222:223], v[94:97], off offset:16
	global_store_dwordx4 v[222:223], v[86:89], off offset:128
	global_store_dwordx4 v[222:223], v[74:77], off offset:144
	global_store_dwordx4 v[226:227], v[82:85], off
	global_store_dwordx4 v[226:227], v[78:81], off offset:16
	global_store_dwordx4 v[226:227], v[70:73], off offset:128
	global_store_dwordx4 v[226:227], v[66:69], off offset:144
	s_waitcnt vmcnt(8)
	v_pk_add_f32 v[62:63], v[62:63], v[164:165]
	v_pk_add_f32 v[64:65], v[64:65], v[166:167]
	v_pk_add_f32 v[58:59], v[58:59], v[168:169]
	v_pk_add_f32 v[60:61], v[60:61], v[170:171]
	v_pk_add_f32 v[54:55], v[54:55], v[172:173]
	v_pk_add_f32 v[56:57], v[56:57], v[174:175]
	v_pk_add_f32 v[42:43], v[42:43], v[176:177]
	v_pk_add_f32 v[44:45], v[44:45], v[178:179]
	v_pk_add_f32 v[50:51], v[50:51], v[180:181]
	v_pk_add_f32 v[52:53], v[52:53], v[182:183]
	v_pk_add_f32 v[46:47], v[46:47], v[184:185]
	v_pk_add_f32 v[48:49], v[48:49], v[186:187]
	v_pk_add_f32 v[38:39], v[38:39], v[188:189]
	v_pk_add_f32 v[40:41], v[40:41], v[190:191]
	v_pk_add_f32 v[26:27], v[26:27], v[192:193]
	v_pk_add_f32 v[28:29], v[28:29], v[194:195]
	v_add_u32_e32 v220, 0xa0, v142
	v_ashrrev_i32_e32 v221, 31, v220
	v_lshlrev_b64 v[220:221], 10, v[220:221]
	v_lshl_add_u64 v[220:221], v[220:221], 0, v[140:141]
	v_lshlrev_b64 v[222:223], 2, v[220:221]
	v_lshl_add_u64 v[220:221], s[24:25], 0, v[222:223]
	v_lshl_add_u64 v[222:223], s[34:35], 0, v[222:223]
	global_load_dwordx4 v[164:167], v[220:221], off
	global_load_dwordx4 v[168:171], v[220:221], off offset:16
	global_load_dwordx4 v[172:175], v[220:221], off offset:128
	global_load_dwordx4 v[176:179], v[220:221], off offset:144
	v_add_u32_e32 v224, 0xb0, v142
	v_ashrrev_i32_e32 v225, 31, v224
	v_lshlrev_b64 v[224:225], 10, v[224:225]
	v_lshl_add_u64 v[224:225], v[224:225], 0, v[140:141]
	v_lshlrev_b64 v[226:227], 2, v[224:225]
	v_lshl_add_u64 v[224:225], s[24:25], 0, v[226:227]
	v_lshl_add_u64 v[226:227], s[34:35], 0, v[226:227]
	global_load_dwordx4 v[180:183], v[224:225], off
	global_load_dwordx4 v[184:187], v[224:225], off offset:16
	global_load_dwordx4 v[188:191], v[224:225], off offset:128
	global_load_dwordx4 v[192:195], v[224:225], off offset:144
	global_store_dwordx4 v[214:215], v[62:65], off
	global_store_dwordx4 v[214:215], v[58:61], off offset:16
	global_store_dwordx4 v[214:215], v[54:57], off offset:128
	global_store_dwordx4 v[214:215], v[42:45], off offset:144
	global_store_dwordx4 v[218:219], v[50:53], off
	global_store_dwordx4 v[218:219], v[46:49], off offset:16
	global_store_dwordx4 v[218:219], v[38:41], off offset:128
	global_store_dwordx4 v[218:219], v[26:29], off offset:144
	s_waitcnt vmcnt(8)
	v_pk_add_f32 v[34:35], v[34:35], v[164:165]
	v_pk_add_f32 v[36:37], v[36:37], v[166:167]
	v_pk_add_f32 v[30:31], v[30:31], v[168:169]
	v_pk_add_f32 v[32:33], v[32:33], v[170:171]
	v_pk_add_f32 v[22:23], v[22:23], v[172:173]
	v_pk_add_f32 v[24:25], v[24:25], v[174:175]
	v_pk_add_f32 v[10:11], v[10:11], v[176:177]
	v_pk_add_f32 v[12:13], v[12:13], v[178:179]
	v_pk_add_f32 v[18:19], v[18:19], v[180:181]
	v_pk_add_f32 v[20:21], v[20:21], v[182:183]
	v_pk_add_f32 v[14:15], v[14:15], v[184:185]
	v_pk_add_f32 v[16:17], v[16:17], v[186:187]
	v_pk_add_f32 v[6:7], v[6:7], v[188:189]
	v_pk_add_f32 v[8:9], v[8:9], v[190:191]
	v_pk_add_f32 v[2:3], v[2:3], v[192:193]
	v_pk_add_f32 v[4:5], v[4:5], v[194:195]
	global_store_dwordx4 v[222:223], v[34:37], off
	global_store_dwordx4 v[222:223], v[30:33], off offset:16
	global_store_dwordx4 v[222:223], v[22:25], off offset:128
	global_store_dwordx4 v[222:223], v[10:13], off offset:144
	global_store_dwordx4 v[226:227], v[18:21], off
	global_store_dwordx4 v[226:227], v[14:17], off offset:16
	global_store_dwordx4 v[226:227], v[6:9], off offset:128
	global_store_dwordx4 v[226:227], v[2:5], off offset:144
	s_cbranch_vccnz .LBB0_546
	s_andn2_b64 vcc, exec, s[8:9]
	s_cbranch_vccnz .LBB0_545
	s_barrier
	s_branch .LBB0_545

;     __device__ __forceinline__ void operator()(AccRef acc, const pg8::Unit& u, int wr, int wc, int fr, int fq) const {
;         const int lc = u.pn * 256 + wc * 64 + fq * 8;
;         const float* sb = (u.pm >= 128) ? srcS - (size_t)MP * 1024 : srcP;
; #pragma unroll
;         for (int ai = 0; ai < 2; ++ai)
; #pragma unroll
;             for (int m = 0; m < 4; ++m) {
;                 const size_t off = (size_t)(u.pm * 256 + ai * 128 + wr * 64 + m * 16 + fr) * 1024 + lc;
; #pragma unroll
;                 for (int bj = 0; bj < 2; ++bj)
; #pragma unroll
;                     for (int n = 0; n < 2; ++n) { const f32x4 s = *(const f32x4*)(sb + off + bj * 32 + n * 4); *(f32x4*)(dst + off + bj * 32 + n * 4) = s + acc[ai][bj][m][n]; }
;             }
.LBB0_650:
	v_lshl_add_u32 v142, s57, 8, v144
	v_lshl_or_b32 v140, s56, 8, v162
	v_ashrrev_i32_e32 v143, 31, v142
	v_ashrrev_i32_e32 v141, 31, v140
	s_andn2_b64 vcc, exec, s[4:5]
	s_mov_b64 s[4:5], -1
	v_lshlrev_b64 v[212:213], 10, v[142:143]
	v_lshl_add_u64 v[212:213], v[212:213], 0, v[140:141]
	v_lshlrev_b64 v[214:215], 2, v[212:213]
	v_lshl_add_u64 v[212:213], s[34:35], 0, v[214:215]
	v_lshl_add_u64 v[214:215], s[22:23], 0, v[214:215]
	global_load_dwordx4 v[164:167], v[212:213], off
	global_load_dwordx4 v[168:171], v[212:213], off offset:16
	global_load_dwordx4 v[172:175], v[212:213], off offset:128
	global_load_dwordx4 v[176:179], v[212:213], off offset:144
	v_add_u32_e32 v216, 0x10, v142
	v_ashrrev_i32_e32 v217, 31, v216
	v_lshlrev_b64 v[216:217], 10, v[216:217]
	v_lshl_add_u64 v[216:217], v[216:217], 0, v[140:141]
	v_lshlrev_b64 v[218:219], 2, v[216:217]
	v_lshl_add_u64 v[216:217], s[34:35], 0, v[218:219]
	v_lshl_add_u64 v[218:219], s[22:23], 0, v[218:219]
	global_load_dwordx4 v[180:183], v[216:217], off
	global_load_dwordx4 v[184:187], v[216:217], off offset:16
	global_load_dwordx4 v[188:191], v[216:217], off offset:128
	global_load_dwordx4 v[192:195], v[216:217], off offset:144
	s_waitcnt vmcnt(0)
	v_pk_add_f32 v[126:127], v[126:127], v[164:165]
	v_pk_add_f32 v[128:129], v[128:129], v[166:167]
	v_pk_add_f32 v[122:123], v[122:123], v[168:169]
	v_pk_add_f32 v[124:125], v[124:125], v[170:171]
	v_pk_add_f32 v[118:119], v[118:119], v[172:173]
	v_pk_add_f32 v[120:121], v[120:121], v[174:175]
	v_pk_add_f32 v[106:107], v[106:107], v[176:177]
	v_pk_add_f32 v[108:109], v[108:109], v[178:179]
	v_pk_add_f32 v[114:115], v[114:115], v[180:181]
	v_pk_add_f32 v[116:117], v[116:117], v[182:183]
	v_pk_add_f32 v[110:111], v[110:111], v[184:185]
	v_pk_add_f32 v[112:113], v[112:113], v[186:187]
	v_pk_add_f32 v[102:103], v[102:103], v[188:189]
	v_pk_add_f32 v[104:105], v[104:105], v[190:191]
	v_pk_add_f32 v[90:91], v[90:91], v[192:193]
	v_pk_add_f32 v[92:93], v[92:93], v[194:195]
	v_add_u32_e32 v220, 0x20, v142
	v_ashrrev_i32_e32 v221, 31, v220
	v_lshlrev_b64 v[220:221], 10, v[220:221]
	v_lshl_add_u64 v[220:221], v[220:221], 0, v[140:141]
	v_lshlrev_b64 v[222:223], 2, v[220:221]
	v_lshl_add_u64 v[220:221], s[34:35], 0, v[222:223]
	v_lshl_add_u64 v[222:223], s[22:23], 0, v[222:223]
	global_load_dwordx4 v[164:167], v[220:221], off
	global_load_dwordx4 v[168:171], v[220:221], off offset:16
	global_load_dwordx4 v[172:175], v[220:221], off offset:128
	global_load_dwordx4 v[176:179], v[220:221], off offset:144
	v_add_u32_e32 v224, 0x30, v142
	v_ashrrev_i32_e32 v225, 31, v224
	v_lshlrev_b64 v[224:225], 10, v[224:225]
	v_lshl_add_u64 v[224:225], v[224:225], 0, v[140:141]
	v_lshlrev_b64 v[226:227], 2, v[224:225]
	v_lshl_add_u64 v[224:225], s[34:35], 0, v[226:227]
	v_lshl_add_u64 v[226:227], s[22:23], 0, v[226:227]
	global_load_dwordx4 v[180:183], v[224:225], off
	global_load_dwordx4 v[184:187], v[224:225], off offset:16
	global_load_dwordx4 v[188:191], v[224:225], off offset:128
	global_load_dwordx4 v[192:195], v[224:225], off offset:144
	global_store_dwordx4 v[214:215], v[126:129], off
	global_store_dwordx4 v[214:215], v[122:125], off offset:16
	global_store_dwordx4 v[214:215], v[118:121], off offset:128
	global_store_dwordx4 v[214:215], v[106:109], off offset:144
	global_store_dwordx4 v[218:219], v[114:117], off
	global_store_dwordx4 v[218:219], v[110:113], off offset:16
	global_store_dwordx4 v[218:219], v[102:105], off offset:128
	global_store_dwordx4 v[218:219], v[90:93], off offset:144
	s_waitcnt vmcnt(8)
;     __device__ __forceinline__ void operator()(AccRef acc, const pg8::Unit& u, int wr, int wc, int fr, int fq) const {
;         const int lc = u.pn * 256 + wc * 64 + fq * 8;
;         const float* sb = (u.pm >= 128) ? srcS - (size_t)MP * 1024 : srcP;
; #pragma unroll
;         for (int ai = 0; ai < 2; ++ai)
; #pragma unroll
;             for (int m = 0; m < 4; ++m) {
;                 const size_t off = (size_t)(u.pm * 256 + ai * 128 + wr * 64 + m * 16 + fr) * 1024 + lc;
; #pragma unroll
;                 for (int bj = 0; bj < 2; ++bj)
; #pragma unroll
;                     for (int n = 0; n < 2; ++n) { const f32x4 s = *(const f32x4*)(sb + off + bj * 32 + n * 4); *(f32x4*)(dst + off + bj * 32 + n * 4) = s + acc[ai][bj][m][n]; }
;             }
	v_pk_add_f32 v[98:99], v[98:99], v[164:165]
	v_pk_add_f32 v[100:101], v[100:101], v[166:167]
	v_pk_add_f32 v[94:95], v[94:95], v[168:169]
	v_pk_add_f32 v[96:97], v[96:97], v[170:171]
	v_pk_add_f32 v[86:87], v[86:87], v[172:173]
	v_pk_add_f32 v[88:89], v[88:89], v[174:175]
	v_pk_add_f32 v[74:75], v[74:75], v[176:177]
	v_pk_add_f32 v[76:77], v[76:77], v[178:179]
	v_pk_add_f32 v[82:83], v[82:83], v[180:181]
	v_pk_add_f32 v[84:85], v[84:85], v[182:183]
	v_pk_add_f32 v[78:79], v[78:79], v[184:185]
	v_pk_add_f32 v[80:81], v[80:81], v[186:187]
	v_pk_add_f32 v[70:71], v[70:71], v[188:189]
	v_pk_add_f32 v[72:73], v[72:73], v[190:191]
	v_pk_add_f32 v[66:67], v[66:67], v[192:193]
	v_pk_add_f32 v[68:69], v[68:69], v[194:195]
	v_add_u32_e32 v212, 0x80, v142
	v_ashrrev_i32_e32 v213, 31, v212
	v_lshlrev_b64 v[212:213], 10, v[212:213]
	v_lshl_add_u64 v[212:213], v[212:213], 0, v[140:141]
	v_lshlrev_b64 v[214:215], 2, v[212:213]
	v_lshl_add_u64 v[212:213], s[34:35], 0, v[214:215]
	v_lshl_add_u64 v[214:215], s[22:23], 0, v[214:215]
	global_load_dwordx4 v[164:167], v[212:213], off
	global_load_dwordx4 v[168:171], v[212:213], off offset:16
	global_load_dwordx4 v[172:175], v[212:213], off offset:128
	global_load_dwordx4 v[176:179], v[212:213], off offset:144
	v_add_u32_e32 v216, 0x90, v142
	v_ashrrev_i32_e32 v217, 31, v216
	v_lshlrev_b64 v[216:217], 10, v[216:217]
	v_lshl_add_u64 v[216:217], v[216:217], 0, v[140:141]
	v_lshlrev_b64 v[218:219], 2, v[216:217]
	v_lshl_add_u64 v[216:217], s[34:35], 0, v[218:219]
	v_lshl_add_u64 v[218:219], s[22:23], 0, v[218:219]
	global_load_dwordx4 v[180:183], v[216:217], off
	global_load_dwordx4 v[184:187], v[216:217], off offset:16
	global_load_dwordx4 v[188:191], v[216:217], off offset:128
	global_load_dwordx4 v[192:195], v[216:217], off offset:144
	global_store_dwordx4 v[222:223], v[98:101], off
	global_store_dwordx4 v[222:223], v[94:97], off offset:16
	global_store_dwordx4 v[222:223], v[86:89], off offset:128
	global_store_dwordx4 v[222:223], v[74:77], off offset:144
	global_store_dwordx4 v[226:227], v[82:85], off
	global_store_dwordx4 v[226:227], v[78:81], off offset:16
	global_store_dwordx4 v[226:227], v[70:73], off offset:128
	global_store_dwordx4 v[226:227], v[66:69], off offset:144
	s_waitcnt vmcnt(8)
	v_pk_add_f32 v[62:63], v[62:63], v[164:165]
	v_pk_add_f32 v[64:65], v[64:65], v[166:167]
	v_pk_add_f32 v[58:59], v[58:59], v[168:169]
	v_pk_add_f32 v[60:61], v[60:61], v[170:171]
	v_pk_add_f32 v[54:55], v[54:55], v[172:173]
	v_pk_add_f32 v[56:57], v[56:57], v[174:175]
	v_pk_add_f32 v[42:43], v[42:43], v[176:177]
	v_pk_add_f32 v[44:45], v[44:45], v[178:179]
	v_pk_add_f32 v[50:51], v[50:51], v[180:181]
	v_pk_add_f32 v[52:53], v[52:53], v[182:183]
	v_pk_add_f32 v[46:47], v[46:47], v[184:185]
	v_pk_add_f32 v[48:49], v[48:49], v[186:187]
	v_pk_add_f32 v[38:39], v[38:39], v[188:189]
	v_pk_add_f32 v[40:41], v[40:41], v[190:191]
	v_pk_add_f32 v[26:27], v[26:27], v[192:193]
	v_pk_add_f32 v[28:29], v[28:29], v[194:195]
	v_add_u32_e32 v220, 0xa0, v142
	v_ashrrev_i32_e32 v221, 31, v220
	v_lshlrev_b64 v[220:221], 10, v[220:221]
	v_lshl_add_u64 v[220:221], v[220:221], 0, v[140:141]
	v_lshlrev_b64 v[222:223], 2, v[220:221]
	v_lshl_add_u64 v[220:221], s[34:35], 0, v[222:223]
	v_lshl_add_u64 v[222:223], s[22:23], 0, v[222:223]
	global_load_dwordx4 v[164:167], v[220:221], off
	global_load_dwordx4 v[168:171], v[220:221], off offset:16
	global_load_dwordx4 v[172:175], v[220:221], off offset:128
	global_load_dwordx4 v[176:179], v[220:221], off offset:144
	v_add_u32_e32 v224, 0xb0, v142
	v_ashrrev_i32_e32 v225, 31, v224
	v_lshlrev_b64 v[224:225], 10, v[224:225]
	v_lshl_add_u64 v[224:225], v[224:225], 0, v[140:141]
	v_lshlrev_b64 v[226:227], 2, v[224:225]
	v_lshl_add_u64 v[224:225], s[34:35], 0, v[226:227]
	v_lshl_add_u64 v[226:227], s[22:23], 0, v[226:227]
	global_load_dwordx4 v[180:183], v[224:225], off
	global_load_dwordx4 v[184:187], v[224:225], off offset:16
	global_load_dwordx4 v[188:191], v[224:225], off offset:128
	global_load_dwordx4 v[192:195], v[224:225], off offset:144
	global_store_dwordx4 v[214:215], v[62:65], off
	global_store_dwordx4 v[214:215], v[58:61], off offset:16
	global_store_dwordx4 v[214:215], v[54:57], off offset:128
	global_store_dwordx4 v[214:215], v[42:45], off offset:144
	global_store_dwordx4 v[218:219], v[50:53], off
	global_store_dwordx4 v[218:219], v[46:49], off offset:16
	global_store_dwordx4 v[218:219], v[38:41], off offset:128
	global_store_dwordx4 v[218:219], v[26:29], off offset:144
	s_waitcnt vmcnt(8)
	v_pk_add_f32 v[34:35], v[34:35], v[164:165]
	v_pk_add_f32 v[36:37], v[36:37], v[166:167]
	v_pk_add_f32 v[30:31], v[30:31], v[168:169]
	v_pk_add_f32 v[32:33], v[32:33], v[170:171]
	v_pk_add_f32 v[22:23], v[22:23], v[172:173]
	v_pk_add_f32 v[24:25], v[24:25], v[174:175]
	v_pk_add_f32 v[10:11], v[10:11], v[176:177]
	v_pk_add_f32 v[12:13], v[12:13], v[178:179]
	v_pk_add_f32 v[18:19], v[18:19], v[180:181]
	v_pk_add_f32 v[20:21], v[20:21], v[182:183]
	v_pk_add_f32 v[14:15], v[14:15], v[184:185]
	v_pk_add_f32 v[16:17], v[16:17], v[186:187]
	v_pk_add_f32 v[6:7], v[6:7], v[188:189]
	v_pk_add_f32 v[8:9], v[8:9], v[190:191]
	v_pk_add_f32 v[2:3], v[2:3], v[192:193]
	v_pk_add_f32 v[4:5], v[4:5], v[194:195]
	global_store_dwordx4 v[222:223], v[34:37], off
	global_store_dwordx4 v[222:223], v[30:33], off offset:16
	global_store_dwordx4 v[222:223], v[22:25], off offset:128
	global_store_dwordx4 v[222:223], v[10:13], off offset:144
	global_store_dwordx4 v[226:227], v[18:21], off
	global_store_dwordx4 v[226:227], v[14:17], off offset:16
	global_store_dwordx4 v[226:227], v[6:9], off offset:128
	global_store_dwordx4 v[226:227], v[2:5], off offset:144
	s_cbranch_vccnz .LBB0_639
	s_andn2_b64 vcc, exec, s[0:1]
	s_cbranch_vccnz .LBB0_638
	s_barrier
	s_branch .LBB0_638
